# attention KV loop: the 8 PV MFMAs are issued inside the softmax exp/cvt stream (each MFMA pair right after its P fragment is packed) instead of after all 32 exps
# speedup vs baseline: 1.0148x; 1.0148x over previous
.LBB0_887:
	v_exp_f32_e32 v0, v50
	v_exp_f32_e32 v50, v51
	v_exp_f32_e32 v51, v52
	v_exp_f32_e32 v52, v53
	v_exp_f32_e32 v53, v54
	v_exp_f32_e32 v54, v55
	v_exp_f32_e32 v55, v56
	v_exp_f32_e32 v56, v57
	v_cvt_pk_bf16_f32 v174, v0, v50
	v_cvt_pk_bf16_f32 v175, v51, v52
	v_cvt_pk_bf16_f32 v176, v53, v54
	v_cvt_pk_bf16_f32 v177, v55, v56
	v_exp_f32_e32 v57, v58
	v_exp_f32_e32 v58, v59
	v_mfma_f32_32x32x16_bf16 v[2:17], v[126:129], v[174:177], v[2:17]
	v_mfma_f32_32x32x16_bf16 v[18:33], v[122:125], v[174:177], v[18:33]
	v_exp_f32_e32 v59, v60
	v_exp_f32_e32 v60, v61
	v_exp_f32_e32 v61, v62
	v_exp_f32_e32 v62, v63
	v_exp_f32_e32 v63, v64
	v_exp_f32_e32 v64, v65
	v_cvt_pk_bf16_f32 v178, v57, v58
	v_cvt_pk_bf16_f32 v179, v59, v60
	v_cvt_pk_bf16_f32 v180, v61, v62
	v_cvt_pk_bf16_f32 v181, v63, v64
	v_exp_f32_e32 v34, v34
	v_exp_f32_e32 v35, v35
	v_mfma_f32_32x32x16_bf16 v[2:17], v[114:117], v[178:181], v[2:17]
	v_mfma_f32_32x32x16_bf16 v[18:33], v[118:121], v[178:181], v[18:33]
	v_exp_f32_e32 v36, v36
	v_exp_f32_e32 v37, v37
	v_exp_f32_e32 v38, v38
	v_exp_f32_e32 v39, v39
	v_exp_f32_e32 v40, v40
	v_exp_f32_e32 v41, v41
	v_cvt_pk_bf16_f32 v182, v34, v35
	v_cvt_pk_bf16_f32 v183, v36, v37
	v_cvt_pk_bf16_f32 v184, v38, v39
	v_cvt_pk_bf16_f32 v185, v40, v41
	v_exp_f32_e32 v42, v42
	v_exp_f32_e32 v43, v43
	v_mfma_f32_32x32x16_bf16 v[2:17], v[110:113], v[182:185], v[2:17]
	v_mfma_f32_32x32x16_bf16 v[18:33], v[106:109], v[182:185], v[18:33]
	v_exp_f32_e32 v44, v44
	v_exp_f32_e32 v45, v45
	v_exp_f32_e32 v46, v46
	v_exp_f32_e32 v47, v47
	v_exp_f32_e32 v48, v48
	v_exp_f32_e32 v49, v49
	v_cvt_pk_bf16_f32 v186, v42, v43
	v_cvt_pk_bf16_f32 v187, v44, v45
	v_cvt_pk_bf16_f32 v188, v46, v47
	v_cvt_pk_bf16_f32 v189, v48, v49
	s_nop 1
	v_mfma_f32_32x32x16_bf16 v[2:17], v[102:105], v[186:189], v[2:17]
	v_mfma_f32_32x32x16_bf16 v[18:33], v[98:101], v[186:189], v[18:33]
	s_movk_i32 s0, 0x6a00
	v_add3_u32 v65, v169, v132, s0
	s_cmp_gt_u32 s17, 32
	ds_write_b128 v171, v[86:89] offset:17920
	ds_write2_b64 v65, v[94:95], v[96:97] offset1:1
	s_waitcnt lgkmcnt(0)
	s_barrier
	s_cbranch_scc1 .LBB0_889
	v_add_co_u32_e32 v86, vcc, 0x1370c000, v164
	s_nop 1
	v_addc_co_u32_e32 v87, vcc, 0, v165, vcc
	v_add_co_u32_e32 v94, vcc, 0x14000000, v162
	global_load_dwordx4 v[86:89], v[86:87], off
	s_nop 0
	v_addc_co_u32_e32 v95, vcc, 0, v163, vcc
	global_load_dwordx4 v[94:97], v[94:95], off offset:384

.LBB0_891:
	v_exp_f32_e32 v50, v50
	v_exp_f32_e32 v51, v51
	v_exp_f32_e32 v52, v52
	v_exp_f32_e32 v53, v53
	v_exp_f32_e32 v54, v54
	v_exp_f32_e32 v55, v55
	v_exp_f32_e32 v56, v56
	v_exp_f32_e32 v57, v57
	v_cvt_pk_bf16_f32 v162, v50, v51
	v_cvt_pk_bf16_f32 v163, v52, v53
	v_cvt_pk_bf16_f32 v164, v54, v55
	v_cvt_pk_bf16_f32 v165, v56, v57
	v_exp_f32_e32 v58, v58
	v_exp_f32_e32 v59, v59
	v_mfma_f32_32x32x16_bf16 v[2:17], v[126:129], v[162:165], v[2:17]
	v_mfma_f32_32x32x16_bf16 v[18:33], v[122:125], v[162:165], v[18:33]
	v_exp_f32_e32 v60, v60
	v_exp_f32_e32 v61, v61
	v_exp_f32_e32 v62, v62
	v_exp_f32_e32 v63, v63
	v_exp_f32_e32 v64, v64
	v_exp_f32_e32 v65, v65
	v_cvt_pk_bf16_f32 v174, v58, v59
	v_cvt_pk_bf16_f32 v175, v60, v61
	v_cvt_pk_bf16_f32 v176, v62, v63
	v_cvt_pk_bf16_f32 v177, v64, v65
	v_exp_f32_e32 v34, v34
	v_exp_f32_e32 v35, v35
	v_mfma_f32_32x32x16_bf16 v[2:17], v[114:117], v[174:177], v[2:17]
	v_mfma_f32_32x32x16_bf16 v[18:33], v[118:121], v[174:177], v[18:33]
	v_exp_f32_e32 v36, v36
	v_exp_f32_e32 v37, v37
	v_exp_f32_e32 v38, v38
	v_exp_f32_e32 v39, v39
	v_exp_f32_e32 v40, v40
	v_exp_f32_e32 v41, v41
	v_cvt_pk_bf16_f32 v178, v34, v35
	v_cvt_pk_bf16_f32 v179, v36, v37
	v_cvt_pk_bf16_f32 v180, v38, v39
	v_cvt_pk_bf16_f32 v181, v40, v41
	v_exp_f32_e32 v42, v42
	v_exp_f32_e32 v43, v43
	v_mfma_f32_32x32x16_bf16 v[2:17], v[110:113], v[178:181], v[2:17]
	v_mfma_f32_32x32x16_bf16 v[18:33], v[106:109], v[178:181], v[18:33]
	v_exp_f32_e32 v44, v44
	v_exp_f32_e32 v45, v45
	v_exp_f32_e32 v46, v46
	v_exp_f32_e32 v47, v47
	v_exp_f32_e32 v48, v48
	v_exp_f32_e32 v49, v49
	v_cvt_pk_bf16_f32 v182, v42, v43
	v_cvt_pk_bf16_f32 v183, v44, v45
	v_cvt_pk_bf16_f32 v184, v46, v47
	v_cvt_pk_bf16_f32 v185, v48, v49
	s_nop 1
	v_mfma_f32_32x32x16_bf16 v[2:17], v[102:105], v[182:185], v[2:17]
	v_mfma_f32_32x32x16_bf16 v[18:33], v[98:101], v[182:185], v[18:33]
	s_andn2_b64 vcc, exec, s[14:15]
	s_cbranch_vccnz .LBB0_882
	ds_write_b128 v171, v[74:77]
	ds_write2_b64 v149, v[90:91], v[92:93] offset1:1
	s_branch .LBB0_882
